# v113 + non-temporal hint on the final f32 output stores of the last GEMM epilogue
# baseline (speedup 1.0000x reference)
.LBB0_1477:
	global_load_dword v180, v[112:113], off sc1
	v_lshlrev_b64 v[160:161], 2, v[142:143]
	v_lshl_add_u64 v[142:143], s[80:81], 0, v[160:161]
	s_waitcnt lgkmcnt(0)
	global_load_dwordx4 v[172:175], v[142:143], off
	global_load_dwordx4 v[176:179], v[142:143], off offset:16
	v_lshlrev_b64 v[140:141], 13, v[140:141]
	v_lshl_add_u64 v[140:141], s[82:83], 0, v[140:141]
	v_lshl_add_u64 v[140:141], v[140:141], 0, v[160:161]
	v_lshlrev_b64 v[122:123], 13, v[122:123]
	v_lshl_add_u64 v[122:123], s[82:83], 0, v[122:123]
	v_lshl_add_u64 v[122:123], v[122:123], 0, v[160:161]
	v_lshlrev_b64 v[104:105], 13, v[104:105]
	v_lshl_add_u64 v[104:105], s[82:83], 0, v[104:105]
	v_lshl_add_u64 v[104:105], v[104:105], 0, v[160:161]
	v_lshlrev_b64 v[88:89], 13, v[88:89]
	v_lshl_add_u64 v[88:89], s[82:83], 0, v[88:89]
	v_lshl_add_u64 v[88:89], v[88:89], 0, v[160:161]
	v_lshlrev_b64 v[72:73], 13, v[72:73]
	v_lshl_add_u64 v[72:73], s[82:83], 0, v[72:73]
	v_lshl_add_u64 v[72:73], v[72:73], 0, v[160:161]
	v_lshlrev_b64 v[56:57], 13, v[56:57]
	v_lshl_add_u64 v[56:57], s[82:83], 0, v[56:57]
	v_lshl_add_u64 v[56:57], v[56:57], 0, v[160:161]
	v_lshlrev_b64 v[40:41], 13, v[40:41]
	v_lshl_add_u64 v[40:41], s[82:83], 0, v[40:41]
	v_lshl_add_u64 v[40:41], v[40:41], 0, v[160:161]
	v_lshlrev_b64 v[24:25], 13, v[24:25]
	v_lshl_add_u64 v[24:25], s[82:83], 0, v[24:25]
	v_lshl_add_u64 v[24:25], v[24:25], 0, v[160:161]
	s_mov_b64 s[0:1], -1
	s_waitcnt vmcnt(2)
	v_fmamk_f32 v180, v180, 0x3a000000, v171
	v_mul_f32_e32 v181, 0x4b800000, v180
	v_cmp_gt_f32_e32 vcc, s44, v180
	s_nop 1
	v_cndmask_b32_e32 v180, v180, v181, vcc
	v_rsq_f32_e32 v180, v180
	s_nop 0
	v_mul_f32_e32 v181, 0x45800000, v180
	v_cndmask_b32_e32 v180, v180, v181, vcc
	v_pk_mul_f32 v[146:147], v[146:147], v[180:181] op_sel_hi:[1,0]
	v_pk_mul_f32 v[144:145], v[144:145], v[180:181] op_sel_hi:[1,0]
	v_pk_mul_f32 v[182:183], v[126:127], v[180:181] op_sel_hi:[1,0]
	v_pk_mul_f32 v[184:185], v[124:125], v[180:181] op_sel_hi:[1,0]
	s_waitcnt vmcnt(1)
	v_pk_mul_f32 v[126:127], v[174:175], v[144:145]
	v_pk_mul_f32 v[124:125], v[172:173], v[146:147]
	s_waitcnt vmcnt(0)
	v_pk_mul_f32 v[146:147], v[178:179], v[184:185]
	v_pk_mul_f32 v[144:145], v[176:177], v[182:183]
	global_store_dwordx4 v[140:141], v[124:127], off nt
	global_store_dwordx4 v[140:141], v[144:147], off offset:16 nt
	global_load_dwordx4 v[124:127], v[142:143], off offset:512
	s_nop 0
	global_load_dwordx4 v[144:147], v[142:143], off offset:528
	v_pk_mul_f32 v[118:119], v[118:119], v[180:181] op_sel_hi:[1,0]
	v_pk_mul_f32 v[120:121], v[120:121], v[180:181] op_sel_hi:[1,0]
	v_pk_mul_f32 v[172:173], v[114:115], v[180:181] op_sel_hi:[1,0]
	v_pk_mul_f32 v[174:175], v[116:117], v[180:181] op_sel_hi:[1,0]
	s_waitcnt vmcnt(1)
	v_pk_mul_f32 v[114:115], v[124:125], v[120:121]
	v_pk_mul_f32 v[116:117], v[126:127], v[118:119]
	s_waitcnt vmcnt(0)
	v_pk_mul_f32 v[118:119], v[144:145], v[174:175]
	v_pk_mul_f32 v[120:121], v[146:147], v[172:173]
	global_store_dwordx4 v[140:141], v[114:117], off offset:512 nt
	global_store_dwordx4 v[140:141], v[118:121], off offset:528 nt
	global_load_dword v124, v[112:113], off offset:64 sc1
	s_nop 0
	global_load_dwordx4 v[114:117], v[142:143], off
	global_load_dwordx4 v[118:121], v[142:143], off offset:16
	s_waitcnt vmcnt(2)
	v_fmamk_f32 v124, v124, 0x3a000000, v171
	v_mul_f32_e32 v125, 0x4b800000, v124
	v_cmp_gt_f32_e32 vcc, s44, v124
	s_nop 1
	v_cndmask_b32_e32 v124, v124, v125, vcc
	v_rsq_f32_e32 v124, v124
	s_nop 0
	v_mul_f32_e32 v125, 0x45800000, v124
	v_cndmask_b32_e32 v124, v124, v125, vcc
	v_pk_mul_f32 v[126:127], v[148:149], v[124:125] op_sel_hi:[1,0]
	v_pk_mul_f32 v[110:111], v[110:111], v[124:125] op_sel_hi:[1,0]
	v_pk_mul_f32 v[140:141], v[108:109], v[124:125] op_sel_hi:[1,0]
	v_pk_mul_f32 v[144:145], v[106:107], v[124:125] op_sel_hi:[1,0]
	s_waitcnt vmcnt(1)
	v_pk_mul_f32 v[108:109], v[116:117], v[110:111]
	v_pk_mul_f32 v[106:107], v[114:115], v[126:127]
	s_waitcnt vmcnt(0)
	v_pk_mul_f32 v[116:117], v[120:121], v[144:145]
	v_pk_mul_f32 v[114:115], v[118:119], v[140:141]
	global_store_dwordx4 v[122:123], v[106:109], off nt
	global_store_dwordx4 v[122:123], v[114:117], off offset:16 nt
	global_load_dwordx4 v[106:109], v[142:143], off offset:512
	s_nop 0
	global_load_dwordx4 v[114:117], v[142:143], off offset:528
	v_pk_mul_f32 v[102:103], v[102:103], v[124:125] op_sel_hi:[1,0]
	v_pk_mul_f32 v[100:101], v[100:101], v[124:125] op_sel_hi:[1,0]
	v_pk_mul_f32 v[110:111], v[98:99], v[124:125] op_sel_hi:[1,0]
	v_pk_mul_f32 v[118:119], v[96:97], v[124:125] op_sel_hi:[1,0]
	s_waitcnt vmcnt(1)
	v_pk_mul_f32 v[96:97], v[106:107], v[100:101]
	v_pk_mul_f32 v[98:99], v[108:109], v[102:103]
	s_waitcnt vmcnt(0)
	v_pk_mul_f32 v[100:101], v[114:115], v[118:119]
	v_pk_mul_f32 v[102:103], v[116:117], v[110:111]
	global_store_dwordx4 v[122:123], v[96:99], off offset:512 nt
	global_store_dwordx4 v[122:123], v[100:103], off offset:528 nt
	global_load_dword v106, v[112:113], off offset:128 sc1
	s_nop 0
	global_load_dwordx4 v[96:99], v[142:143], off
	global_load_dwordx4 v[100:103], v[142:143], off offset:16
	s_waitcnt vmcnt(2)
	v_fmamk_f32 v106, v106, 0x3a000000, v171
	v_mul_f32_e32 v107, 0x4b800000, v106
	v_cmp_gt_f32_e32 vcc, s44, v106
	s_nop 1
	v_cndmask_b32_e32 v106, v106, v107, vcc
	v_rsq_f32_e32 v106, v106
	s_nop 0
	v_mul_f32_e32 v107, 0x45800000, v106
	v_cndmask_b32_e32 v106, v106, v107, vcc
	v_pk_mul_f32 v[108:109], v[150:151], v[106:107] op_sel_hi:[1,0]
	v_pk_mul_f32 v[94:95], v[94:95], v[106:107] op_sel_hi:[1,0]
	v_pk_mul_f32 v[110:111], v[92:93], v[106:107] op_sel_hi:[1,0]
	v_pk_mul_f32 v[114:115], v[90:91], v[106:107] op_sel_hi:[1,0]
	s_waitcnt vmcnt(1)
	v_pk_mul_f32 v[92:93], v[98:99], v[94:95]
	v_pk_mul_f32 v[90:91], v[96:97], v[108:109]
	s_waitcnt vmcnt(0)
	v_pk_mul_f32 v[96:97], v[102:103], v[114:115]
	v_pk_mul_f32 v[94:95], v[100:101], v[110:111]
	global_store_dwordx4 v[104:105], v[90:93], off nt
	global_store_dwordx4 v[104:105], v[94:97], off offset:16 nt
	global_load_dwordx4 v[90:93], v[142:143], off offset:512
	s_nop 0
	global_load_dwordx4 v[94:97], v[142:143], off offset:528
	v_pk_mul_f32 v[86:87], v[86:87], v[106:107] op_sel_hi:[1,0]
	v_pk_mul_f32 v[84:85], v[84:85], v[106:107] op_sel_hi:[1,0]
	v_pk_mul_f32 v[98:99], v[82:83], v[106:107] op_sel_hi:[1,0]
	v_pk_mul_f32 v[100:101], v[80:81], v[106:107] op_sel_hi:[1,0]
	s_waitcnt vmcnt(1)
	v_pk_mul_f32 v[80:81], v[90:91], v[84:85]
	v_pk_mul_f32 v[82:83], v[92:93], v[86:87]
	s_waitcnt vmcnt(0)
	v_pk_mul_f32 v[84:85], v[94:95], v[100:101]
	v_pk_mul_f32 v[86:87], v[96:97], v[98:99]
	global_store_dwordx4 v[104:105], v[80:83], off offset:512 nt
	global_store_dwordx4 v[104:105], v[84:87], off offset:528 nt
	global_load_dword v90, v[112:113], off offset:192 sc1
	s_nop 0
	global_load_dwordx4 v[80:83], v[142:143], off
	global_load_dwordx4 v[84:87], v[142:143], off offset:16
	s_waitcnt vmcnt(2)
	v_fmamk_f32 v90, v90, 0x3a000000, v171
	v_mul_f32_e32 v91, 0x4b800000, v90
	v_cmp_gt_f32_e32 vcc, s44, v90
	s_nop 1
	v_cndmask_b32_e32 v90, v90, v91, vcc
	v_rsq_f32_e32 v90, v90
	s_nop 0
	v_mul_f32_e32 v91, 0x45800000, v90
	v_cndmask_b32_e32 v90, v90, v91, vcc
	v_pk_mul_f32 v[92:93], v[152:153], v[90:91] op_sel_hi:[1,0]
	v_pk_mul_f32 v[78:79], v[78:79], v[90:91] op_sel_hi:[1,0]
	v_pk_mul_f32 v[94:95], v[76:77], v[90:91] op_sel_hi:[1,0]
	v_pk_mul_f32 v[96:97], v[74:75], v[90:91] op_sel_hi:[1,0]
	s_waitcnt vmcnt(1)
	v_pk_mul_f32 v[76:77], v[82:83], v[78:79]
	v_pk_mul_f32 v[74:75], v[80:81], v[92:93]
	s_waitcnt vmcnt(0)
	v_pk_mul_f32 v[80:81], v[86:87], v[96:97]
	v_pk_mul_f32 v[78:79], v[84:85], v[94:95]
	global_store_dwordx4 v[88:89], v[74:77], off nt
	global_store_dwordx4 v[88:89], v[78:81], off offset:16 nt
	global_load_dwordx4 v[74:77], v[142:143], off offset:512
	s_nop 0
	global_load_dwordx4 v[78:81], v[142:143], off offset:528
	v_pk_mul_f32 v[70:71], v[70:71], v[90:91] op_sel_hi:[1,0]
	v_pk_mul_f32 v[68:69], v[68:69], v[90:91] op_sel_hi:[1,0]
	v_pk_mul_f32 v[82:83], v[66:67], v[90:91] op_sel_hi:[1,0]
	v_pk_mul_f32 v[84:85], v[64:65], v[90:91] op_sel_hi:[1,0]
	s_waitcnt vmcnt(1)
	v_pk_mul_f32 v[64:65], v[74:75], v[68:69]
	v_pk_mul_f32 v[66:67], v[76:77], v[70:71]
	s_waitcnt vmcnt(0)
	v_pk_mul_f32 v[68:69], v[78:79], v[84:85]
	v_pk_mul_f32 v[70:71], v[80:81], v[82:83]
	global_store_dwordx4 v[88:89], v[64:67], off offset:512 nt
	global_store_dwordx4 v[88:89], v[68:71], off offset:528 nt
	global_load_dword v74, v[112:113], off offset:512 sc1
	s_nop 0
	global_load_dwordx4 v[64:67], v[142:143], off
	global_load_dwordx4 v[68:71], v[142:143], off offset:16
	s_waitcnt vmcnt(2)
	v_fmamk_f32 v74, v74, 0x3a000000, v171
	v_mul_f32_e32 v75, 0x4b800000, v74
	v_cmp_gt_f32_e32 vcc, s44, v74
	s_nop 1
	v_cndmask_b32_e32 v74, v74, v75, vcc
	v_rsq_f32_e32 v74, v74
	s_nop 0
	v_mul_f32_e32 v75, 0x45800000, v74
	v_cndmask_b32_e32 v74, v74, v75, vcc
	v_pk_mul_f32 v[76:77], v[154:155], v[74:75] op_sel_hi:[1,0]
	v_pk_mul_f32 v[62:63], v[62:63], v[74:75] op_sel_hi:[1,0]
	v_pk_mul_f32 v[78:79], v[60:61], v[74:75] op_sel_hi:[1,0]
	v_pk_mul_f32 v[80:81], v[58:59], v[74:75] op_sel_hi:[1,0]
	s_waitcnt vmcnt(1)
	v_pk_mul_f32 v[60:61], v[66:67], v[62:63]
	v_pk_mul_f32 v[58:59], v[64:65], v[76:77]
	s_waitcnt vmcnt(0)
	v_pk_mul_f32 v[64:65], v[70:71], v[80:81]
	v_pk_mul_f32 v[62:63], v[68:69], v[78:79]
	global_store_dwordx4 v[72:73], v[58:61], off nt
	global_store_dwordx4 v[72:73], v[62:65], off offset:16 nt
	global_load_dwordx4 v[58:61], v[142:143], off offset:512
	s_nop 0
	global_load_dwordx4 v[62:65], v[142:143], off offset:528
	v_pk_mul_f32 v[54:55], v[54:55], v[74:75] op_sel_hi:[1,0]
	v_pk_mul_f32 v[52:53], v[52:53], v[74:75] op_sel_hi:[1,0]
	v_pk_mul_f32 v[66:67], v[50:51], v[74:75] op_sel_hi:[1,0]
	v_pk_mul_f32 v[68:69], v[48:49], v[74:75] op_sel_hi:[1,0]
	s_waitcnt vmcnt(1)
	v_pk_mul_f32 v[48:49], v[58:59], v[52:53]
	v_pk_mul_f32 v[50:51], v[60:61], v[54:55]
	s_waitcnt vmcnt(0)
	v_pk_mul_f32 v[52:53], v[62:63], v[68:69]
	v_pk_mul_f32 v[54:55], v[64:65], v[66:67]
	global_store_dwordx4 v[72:73], v[48:51], off offset:512 nt
	global_store_dwordx4 v[72:73], v[52:55], off offset:528 nt
	global_load_dword v58, v[112:113], off offset:576 sc1
	s_nop 0
	global_load_dwordx4 v[48:51], v[142:143], off
	global_load_dwordx4 v[52:55], v[142:143], off offset:16
	s_waitcnt vmcnt(2)
	v_fmamk_f32 v58, v58, 0x3a000000, v171
	v_mul_f32_e32 v59, 0x4b800000, v58
	v_cmp_gt_f32_e32 vcc, s44, v58
	s_nop 1
	v_cndmask_b32_e32 v58, v58, v59, vcc
	v_rsq_f32_e32 v58, v58
	s_nop 0
	v_mul_f32_e32 v59, 0x45800000, v58
	v_cndmask_b32_e32 v58, v58, v59, vcc
	v_pk_mul_f32 v[60:61], v[156:157], v[58:59] op_sel_hi:[1,0]
	v_pk_mul_f32 v[46:47], v[46:47], v[58:59] op_sel_hi:[1,0]
	v_pk_mul_f32 v[62:63], v[44:45], v[58:59] op_sel_hi:[1,0]
	v_pk_mul_f32 v[64:65], v[42:43], v[58:59] op_sel_hi:[1,0]
	s_waitcnt vmcnt(1)
	v_pk_mul_f32 v[44:45], v[50:51], v[46:47]
	v_pk_mul_f32 v[42:43], v[48:49], v[60:61]
	s_waitcnt vmcnt(0)
	v_pk_mul_f32 v[48:49], v[54:55], v[64:65]
	v_pk_mul_f32 v[46:47], v[52:53], v[62:63]
	global_store_dwordx4 v[56:57], v[42:45], off nt
	global_store_dwordx4 v[56:57], v[46:49], off offset:16 nt
	global_load_dwordx4 v[42:45], v[142:143], off offset:512
	s_nop 0
	global_load_dwordx4 v[46:49], v[142:143], off offset:528
	v_pk_mul_f32 v[38:39], v[38:39], v[58:59] op_sel_hi:[1,0]
	v_pk_mul_f32 v[36:37], v[36:37], v[58:59] op_sel_hi:[1,0]
	v_pk_mul_f32 v[50:51], v[34:35], v[58:59] op_sel_hi:[1,0]
	v_pk_mul_f32 v[52:53], v[32:33], v[58:59] op_sel_hi:[1,0]
	s_waitcnt vmcnt(1)
	v_pk_mul_f32 v[32:33], v[42:43], v[36:37]
	v_pk_mul_f32 v[34:35], v[44:45], v[38:39]
	s_waitcnt vmcnt(0)
	v_pk_mul_f32 v[36:37], v[46:47], v[52:53]
	v_pk_mul_f32 v[38:39], v[48:49], v[50:51]
	global_store_dwordx4 v[56:57], v[32:35], off offset:512 nt
	global_store_dwordx4 v[56:57], v[36:39], off offset:528 nt
	global_load_dword v42, v[112:113], off offset:640 sc1
	s_nop 0
	global_load_dwordx4 v[32:35], v[142:143], off
	global_load_dwordx4 v[36:39], v[142:143], off offset:16
	s_waitcnt vmcnt(2)
	v_fmamk_f32 v42, v42, 0x3a000000, v171
	v_mul_f32_e32 v43, 0x4b800000, v42
	v_cmp_gt_f32_e32 vcc, s44, v42
	s_nop 1
	v_cndmask_b32_e32 v42, v42, v43, vcc
	v_rsq_f32_e32 v42, v42
	s_nop 0
	v_mul_f32_e32 v43, 0x45800000, v42
	v_cndmask_b32_e32 v42, v42, v43, vcc
	v_pk_mul_f32 v[44:45], v[158:159], v[42:43] op_sel_hi:[1,0]
	v_pk_mul_f32 v[30:31], v[30:31], v[42:43] op_sel_hi:[1,0]
	v_pk_mul_f32 v[46:47], v[28:29], v[42:43] op_sel_hi:[1,0]
	v_pk_mul_f32 v[48:49], v[26:27], v[42:43] op_sel_hi:[1,0]
	s_waitcnt vmcnt(1)
	v_pk_mul_f32 v[28:29], v[34:35], v[30:31]
	v_pk_mul_f32 v[26:27], v[32:33], v[44:45]
	s_waitcnt vmcnt(0)
	v_pk_mul_f32 v[32:33], v[38:39], v[48:49]
	v_pk_mul_f32 v[30:31], v[36:37], v[46:47]
	global_store_dwordx4 v[40:41], v[26:29], off nt
	global_store_dwordx4 v[40:41], v[30:33], off offset:16 nt
	global_load_dwordx4 v[26:29], v[142:143], off offset:512
	s_nop 0
	global_load_dwordx4 v[30:33], v[142:143], off offset:528
	v_pk_mul_f32 v[22:23], v[22:23], v[42:43] op_sel_hi:[1,0]
	v_pk_mul_f32 v[20:21], v[20:21], v[42:43] op_sel_hi:[1,0]
	v_pk_mul_f32 v[34:35], v[18:19], v[42:43] op_sel_hi:[1,0]
	v_pk_mul_f32 v[36:37], v[16:17], v[42:43] op_sel_hi:[1,0]
	s_waitcnt vmcnt(1)
	v_pk_mul_f32 v[16:17], v[26:27], v[20:21]
	v_pk_mul_f32 v[18:19], v[28:29], v[22:23]
	s_waitcnt vmcnt(0)
	v_pk_mul_f32 v[20:21], v[30:31], v[36:37]
	v_pk_mul_f32 v[22:23], v[32:33], v[34:35]
	global_store_dwordx4 v[40:41], v[16:19], off offset:512 nt
	global_store_dwordx4 v[40:41], v[20:23], off offset:528 nt
	global_load_dword v26, v[112:113], off offset:704 sc1
	s_nop 0
	global_load_dwordx4 v[16:19], v[142:143], off
	global_load_dwordx4 v[20:23], v[142:143], off offset:16
	s_waitcnt vmcnt(2)
	v_fmamk_f32 v26, v26, 0x3a000000, v171
	v_mul_f32_e32 v27, 0x4b800000, v26
	v_cmp_gt_f32_e32 vcc, s44, v26
	s_nop 1
	v_cndmask_b32_e32 v26, v26, v27, vcc
	v_rsq_f32_e32 v26, v26
	s_nop 0
	v_mul_f32_e32 v27, 0x45800000, v26
	v_cndmask_b32_e32 v26, v26, v27, vcc
	v_pk_mul_f32 v[12:13], v[12:13], v[26:27] op_sel_hi:[1,0]
	v_pk_mul_f32 v[14:15], v[14:15], v[26:27] op_sel_hi:[1,0]
	v_pk_mul_f32 v[28:29], v[8:9], v[26:27] op_sel_hi:[1,0]
	v_pk_mul_f32 v[30:31], v[10:11], v[26:27] op_sel_hi:[1,0]
	s_waitcnt vmcnt(1)
	v_pk_mul_f32 v[10:11], v[18:19], v[14:15]
	v_pk_mul_f32 v[8:9], v[16:17], v[12:13]
	s_waitcnt vmcnt(0)
	v_pk_mul_f32 v[14:15], v[22:23], v[30:31]
	v_pk_mul_f32 v[12:13], v[20:21], v[28:29]
	global_store_dwordx4 v[24:25], v[8:11], off nt
	global_store_dwordx4 v[24:25], v[12:15], off offset:16 nt
	global_load_dwordx4 v[8:11], v[142:143], off offset:512
	s_nop 0
	global_load_dwordx4 v[12:15], v[142:143], off offset:528
	v_pk_mul_f32 v[6:7], v[6:7], v[26:27] op_sel_hi:[1,0]
	v_pk_mul_f32 v[4:5], v[4:5], v[26:27] op_sel_hi:[1,0]
	s_andn2_b64 vcc, exec, s[18:19]
	v_pk_mul_f32 v[16:17], v[2:3], v[26:27] op_sel_hi:[1,0]
	v_pk_mul_f32 v[18:19], v[0:1], v[26:27] op_sel_hi:[1,0]
	s_waitcnt vmcnt(1)
	v_pk_mul_f32 v[0:1], v[8:9], v[4:5]
	v_pk_mul_f32 v[2:3], v[10:11], v[6:7]
	s_waitcnt vmcnt(0)
	v_pk_mul_f32 v[4:5], v[12:13], v[18:19]
	v_pk_mul_f32 v[6:7], v[14:15], v[16:17]
	global_store_dwordx4 v[24:25], v[0:3], off offset:512 nt
	global_store_dwordx4 v[24:25], v[4:7], off offset:528 nt
	s_cbranch_vccnz .LBB0_1433
	s_andn2_b64 vcc, exec, s[4:5]
	s_cbranch_vccnz .LBB0_1432
	s_barrier
	s_branch .LBB0_1432
